# MLA+FoX main loops: all K-fragment ds_reads issued up front into distinct VGPRs (counted lgkmcnt), cross-half row max via v_permlane32_swap instead of ds_bpermute
# baseline (speedup 1.0000x reference)
; template <int MODE>
; __device__ __forceinline__ void attn_unit(const Params& P, int b, int h, int qb, unsigned char* smem) {
;     ...
;         for (int ks = 0; ks < 4; ++ks) {
;           bf16x8 kf = *(const bf16x8*)(smem + cur + (32 * kb + r) * 128 + (((2 * ks + hi) ^ swz) << 4));
;           sacc[kb] = __builtin_amdgcn_mfma_f32_32x32x16_bf16(kf, qf[ks], sacc[kb], 0, 0, 0);
;         }
;         if (MODE == 0) {
; #pragma unroll
;           for (int ks = 0; ks < 2; ++ks) {
;             bf16x8 kf = *(const bf16x8*)(smem + cur + 16384 + (32 * kb + r) * 64 + (((2 * ks + hi) ^ swr) << 4));
;             sacc[kb] = __builtin_amdgcn_mfma_f32_32x32x16_bf16(kf, qf[4 + ks], sacc[kb], 0, 0, 0);
;           }
;         }
;       }
;       if (MODE == 2) {
; #pragma unroll
;         for (int kb = 0; kb < 2; ++kb)
; #pragma unroll
;           for (int i = 0; i < 16; ++i) {
;             const int key = k0 + 32 * kb + 8 * (i >> 2) + 4 * hi + (i & 3);
;             const int dist = qi - key;
;             const float v = sacc[kb][i] - slope2 * (float)dist;
;             sacc[kb][i] = (dist >= 0 && dist < 128) ? v : -INFINITY;
;           }
;       } else if (k0 + 63 > qw0) {
; #pragma unroll
;         for (int kb = 0; kb < 2; ++kb)
; #pragma unroll
;           for (int i = 0; i < 16; ++i) {
;             const int key = k0 + 32 * kb + 8 * (i >> 2) + 4 * hi + (i & 3);
;             if (key > qi) sacc[kb][i] = -INFINITY;
;           }
;       }
.LBB0_848:
	s_or_b64 exec, exec, s[16:17]
	s_bitcmp1_b32 s27, 0
	s_cselect_b32 s28, 0x5100, 0
	v_cmp_le_i32_e32 vcc, s10, v92
	s_and_saveexec_b64 s[16:17], vcc
	s_cbranch_execz .LBB0_854
	s_add_i32 s18, s28, 0
	v_add_u32_e32 v11, s18, v153
	v_add_u32_e32 v13, s18, v148
	v_add_u32_e32 v10, v11, v155
	v_add_u32_e32 v0, v11, v154
	v_add_u32_e32 v12, v11, v152
	v_add_u32_e32 v11, v11, v151
	v_add_u32_e32 v14, v13, v149
	v_add_u32_e32 v13, v13, v150
	ds_read_b128 v[192:195], v10
	ds_read_b128 v[172:175], v0
	ds_read_b128 v[176:179], v12
	ds_read_b128 v[180:183], v11
	ds_read_b128 v[184:187], v14 offset:16384
	ds_read_b128 v[188:191], v13 offset:16384
	ds_read_b128 v[48:51], v10 offset:4096
	ds_read_b128 v[94:97], v0 offset:4096
	ds_read_b128 v[98:101], v12 offset:4096
	ds_read_b128 v[102:105], v11 offset:4096
	ds_read_b128 v[106:109], v14 offset:18432
	ds_read_b128 v[158:161], v13 offset:18432
	s_add_i32 s18, s10, 63
	v_cmp_gt_i32_e32 vcc, s18, v146
	s_waitcnt lgkmcnt(11)
	v_mfma_f32_32x32x16_bf16 v[64:79], v[192:195], v[118:121], 0
	s_waitcnt lgkmcnt(10)
	v_mfma_f32_32x32x16_bf16 v[64:79], v[172:175], v[122:125], v[64:79]
	s_waitcnt lgkmcnt(9)
	v_mfma_f32_32x32x16_bf16 v[64:79], v[176:179], v[126:129], v[64:79]
	s_waitcnt lgkmcnt(8)
	v_mfma_f32_32x32x16_bf16 v[64:79], v[180:183], v[130:133], v[64:79]
	s_waitcnt lgkmcnt(7)
	v_mfma_f32_32x32x16_bf16 v[64:79], v[184:187], v[134:137], v[64:79]
	s_waitcnt lgkmcnt(6)
	v_mfma_f32_32x32x16_bf16 v[64:79], v[188:191], v[114:117], v[64:79]
	s_waitcnt lgkmcnt(5)
	v_mfma_f32_32x32x16_bf16 v[48:63], v[48:51], v[118:121], 0
	s_waitcnt lgkmcnt(4)
	v_mfma_f32_32x32x16_bf16 v[48:63], v[94:97], v[122:125], v[48:63]
	s_waitcnt lgkmcnt(3)
	v_mfma_f32_32x32x16_bf16 v[48:63], v[98:101], v[126:129], v[48:63]
	s_waitcnt lgkmcnt(2)
	v_mfma_f32_32x32x16_bf16 v[48:63], v[102:105], v[130:133], v[48:63]
	s_waitcnt lgkmcnt(1)
	v_mfma_f32_32x32x16_bf16 v[48:63], v[106:109], v[134:137], v[48:63]
	s_waitcnt lgkmcnt(0)
	v_mfma_f32_32x32x16_bf16 v[48:63], v[158:161], v[114:117], v[48:63]
	s_and_saveexec_b64 s[18:19], vcc
	s_cbranch_execz .LBB0_851
	v_add_u32_e32 v13, s10, v144
	v_cmp_gt_i32_e32 vcc, v13, v140
	s_nop 1
	v_cndmask_b32_e32 v14, v64, v143, vcc
	v_cmp_lt_i32_e32 vcc, v13, v140
	s_nop 1
	v_cndmask_b32_e32 v64, v14, v64, vcc
	v_add_u32_e32 v14, 2, v13
	v_cndmask_b32_e32 v65, v143, v65, vcc
	v_cmp_le_i32_e32 vcc, v14, v140
	v_add_u32_e32 v14, 3, v13
	s_nop 0
	v_cndmask_b32_e32 v66, v143, v66, vcc
	v_cmp_le_i32_e32 vcc, v14, v140
	v_add_u32_e32 v14, 8, v13
	s_nop 0
	v_cndmask_b32_e32 v67, v143, v67, vcc
	v_cmp_le_i32_e32 vcc, v14, v140
	v_add_u32_e32 v14, 9, v13
	s_nop 0
	v_cndmask_b32_e32 v68, v143, v68, vcc
	v_cmp_le_i32_e32 vcc, v14, v140
	v_add_u32_e32 v14, 10, v13
	s_nop 0
	v_cndmask_b32_e32 v69, v143, v69, vcc
	v_cmp_le_i32_e32 vcc, v14, v140
	v_add_u32_e32 v14, 11, v13
	s_nop 0
	v_cndmask_b32_e32 v70, v143, v70, vcc
	v_cmp_le_i32_e32 vcc, v14, v140
	v_add_u32_e32 v14, 16, v13
	s_nop 0
	v_cndmask_b32_e32 v71, v143, v71, vcc
	v_cmp_le_i32_e32 vcc, v14, v140
	v_add_u32_e32 v14, 17, v13
	s_nop 0
	v_cndmask_b32_e32 v72, v143, v72, vcc
	v_cmp_le_i32_e32 vcc, v14, v140
	v_add_u32_e32 v14, 18, v13
	s_nop 0
	v_cndmask_b32_e32 v73, v143, v73, vcc
	v_cmp_le_i32_e32 vcc, v14, v140
	v_add_u32_e32 v14, 19, v13
	s_nop 0
	v_cndmask_b32_e32 v74, v143, v74, vcc
	v_cmp_le_i32_e32 vcc, v14, v140
	v_add_u32_e32 v14, 24, v13
	s_nop 0
	v_cndmask_b32_e32 v75, v143, v75, vcc
	v_cmp_le_i32_e32 vcc, v14, v140
	v_add_u32_e32 v14, 25, v13
	s_nop 0
	v_cndmask_b32_e32 v76, v143, v76, vcc
	v_cmp_le_i32_e32 vcc, v14, v140
	v_add_u32_e32 v14, 26, v13
	s_nop 0
	v_cndmask_b32_e32 v77, v143, v77, vcc
	v_cmp_le_i32_e32 vcc, v14, v140
	v_add_u32_e32 v14, 27, v13
	s_nop 0
	v_cndmask_b32_e32 v78, v143, v78, vcc
	v_cmp_le_i32_e32 vcc, v14, v140
	v_add_u32_e32 v14, 32, v13
	s_nop 0
	v_cndmask_b32_e32 v79, v143, v79, vcc
	v_cmp_le_i32_e32 vcc, v14, v140
	v_add_u32_e32 v14, 33, v13
	s_nop 0
	v_cndmask_b32_e32 v48, v143, v48, vcc
	v_cmp_le_i32_e32 vcc, v14, v140
	v_add_u32_e32 v14, 34, v13
	s_nop 0
	v_cndmask_b32_e32 v49, v143, v49, vcc
	v_cmp_le_i32_e32 vcc, v14, v140
	v_add_u32_e32 v14, 35, v13
	s_nop 0
	v_cndmask_b32_e32 v50, v143, v50, vcc
	v_cmp_le_i32_e32 vcc, v14, v140
	v_add_u32_e32 v14, 40, v13
	s_nop 0
	v_cndmask_b32_e32 v51, v143, v51, vcc
	v_cmp_le_i32_e32 vcc, v14, v140
	v_add_u32_e32 v14, 41, v13
	s_nop 0
	v_cndmask_b32_e32 v52, v143, v52, vcc
	v_cmp_le_i32_e32 vcc, v14, v140
	v_add_u32_e32 v14, 42, v13
	s_nop 0
	v_cndmask_b32_e32 v53, v143, v53, vcc
	v_cmp_le_i32_e32 vcc, v14, v140
	v_add_u32_e32 v14, 43, v13
	s_nop 0
	v_cndmask_b32_e32 v54, v143, v54, vcc
	v_cmp_le_i32_e32 vcc, v14, v140
	v_add_u32_e32 v14, 48, v13
	s_nop 0
	v_cndmask_b32_e32 v55, v143, v55, vcc
	v_cmp_le_i32_e32 vcc, v14, v140
	v_add_u32_e32 v14, 49, v13
	s_nop 0
	v_cndmask_b32_e32 v56, v143, v56, vcc
	v_cmp_le_i32_e32 vcc, v14, v140
	v_add_u32_e32 v14, 50, v13
	s_nop 0
	v_cndmask_b32_e32 v57, v143, v57, vcc
	v_cmp_le_i32_e32 vcc, v14, v140
	v_add_u32_e32 v14, 51, v13
	s_nop 0
	v_cndmask_b32_e32 v58, v143, v58, vcc
	v_cmp_le_i32_e32 vcc, v14, v140
	v_add_u32_e32 v14, 56, v13
	s_nop 0
	v_cndmask_b32_e32 v59, v143, v59, vcc
	v_cmp_le_i32_e32 vcc, v14, v140
	v_add_u32_e32 v14, 57, v13
	s_nop 0
	v_cndmask_b32_e32 v60, v143, v60, vcc
	v_cmp_le_i32_e32 vcc, v14, v140
	v_add_u32_e32 v14, 58, v13
	v_add_u32_e32 v13, 59, v13
	v_cndmask_b32_e32 v61, v143, v61, vcc
	v_cmp_le_i32_e32 vcc, v14, v140
	s_nop 1
	v_cndmask_b32_e32 v62, v143, v62, vcc
	v_cmp_le_i32_e32 vcc, v13, v140
	s_nop 1
	v_cndmask_b32_e32 v63, v143, v63, vcc
; __device__ __forceinline__ float fast_exp2(float x) { return __builtin_amdgcn_exp2f(x); }
; template <int MODE>
; __device__ __forceinline__ void attn_unit(const Params& P, int b, int h, int qb, unsigned char* smem) {
;     ...
;       float mx = sacc[0][0];
; #pragma unroll
;       for (int i = 1; i < 16; ++i) mx = fmaxf(mx, sacc[0][i]);
; #pragma unroll
;       for (int i = 0; i < 16; ++i) mx = fmaxf(mx, sacc[1][i]);
;       mx = fmaxf(mx, __shfl_xor(mx, 32));
;       if (__any(mx > m_run + 24.0f)) {
;         const float m_new = fmaxf(m_run, mx);
;         const float alpha = fast_exp2(m_run - m_new);
;         m_run = m_new; l_run *= alpha;
;         const f32x2_t a2 = {alpha, alpha};
; #pragma unroll
;         for (int i = 0; i < 8; ++i) {
;           f32x2_t t0 = {oacc[0][2 * i], oacc[0][2 * i + 1]}, t1 = {oacc[1][2 * i], oacc[1][2 * i + 1]};
;           t0 *= a2; t1 *= a2;
;           oacc[0][2 * i] = t0[0]; oacc[0][2 * i + 1] = t0[1]; oacc[1][2 * i] = t1[0]; oacc[1][2 * i + 1] = t1[1];
;         }
;       }
.LBB0_851:
	s_or_b64 exec, exec, s[18:19]
	s_nop 1
	v_max_f32_e32 v13, v65, v65
	v_max_f32_e32 v14, v64, v64
	v_max_f32_e32 v13, v14, v13
	v_max3_f32 v13, v13, v66, v67
	v_max3_f32 v13, v13, v68, v69
	v_max3_f32 v13, v13, v70, v71
	v_max3_f32 v13, v13, v72, v73
	v_max3_f32 v13, v13, v74, v75
	v_max3_f32 v13, v13, v76, v77
	v_max3_f32 v13, v13, v78, v79
	v_max3_f32 v13, v13, v48, v49
	v_max3_f32 v13, v13, v50, v51
	v_max3_f32 v13, v13, v52, v53
	v_max3_f32 v13, v13, v54, v55
	v_max3_f32 v13, v13, v56, v57
	v_max3_f32 v13, v13, v58, v59
	v_max3_f32 v13, v13, v60, v61
	v_max3_f32 v13, v13, v62, v63
	v_mov_b32_e32 v14, v13
	s_nop 1
	v_permlane32_swap_b32_e32 v14, v13
	v_max_f32_e32 v13, v13, v14
	v_add_f32_e32 v14, 0x41c00000, v142
	v_cmp_gt_f32_e32 vcc, v13, v14
	s_cbranch_vccz .LBB0_853
	v_max_f32_e32 v13, v13, v13
	v_max_f32_e32 v14, v142, v142
	v_max_f32_e32 v13, v14, v13
	v_sub_f32_e32 v14, v142, v13
	v_exp_f32_e32 v14, v14
	v_mov_b32_e32 v142, v13
	v_pk_mul_f32 v[46:47], v[46:47], v[14:15] op_sel_hi:[1,0]
	v_pk_mul_f32 v[44:45], v[44:45], v[14:15] op_sel_hi:[1,0]
	v_pk_mul_f32 v[42:43], v[42:43], v[14:15] op_sel_hi:[1,0]
	v_pk_mul_f32 v[40:41], v[40:41], v[14:15] op_sel_hi:[1,0]
	v_pk_mul_f32 v[38:39], v[38:39], v[14:15] op_sel_hi:[1,0]
	v_pk_mul_f32 v[36:37], v[36:37], v[14:15] op_sel_hi:[1,0]
	v_pk_mul_f32 v[34:35], v[34:35], v[14:15] op_sel_hi:[1,0]
	v_pk_mul_f32 v[32:33], v[32:33], v[14:15] op_sel_hi:[1,0]
	v_pk_mul_f32 v[30:31], v[30:31], v[14:15] op_sel_hi:[1,0]
	v_pk_mul_f32 v[28:29], v[28:29], v[14:15] op_sel_hi:[1,0]
	v_pk_mul_f32 v[26:27], v[26:27], v[14:15] op_sel_hi:[1,0]
	v_pk_mul_f32 v[24:25], v[24:25], v[14:15] op_sel_hi:[1,0]
	v_pk_mul_f32 v[22:23], v[22:23], v[14:15] op_sel_hi:[1,0]
	v_pk_mul_f32 v[20:21], v[20:21], v[14:15] op_sel_hi:[1,0]
	v_pk_mul_f32 v[18:19], v[18:19], v[14:15] op_sel_hi:[1,0]
	v_pk_mul_f32 v[16:17], v[16:17], v[14:15] op_sel_hi:[1,0]
	v_mul_f32_e32 v145, v145, v14

; template <int MODE>
; __device__ __forceinline__ void attn_unit(const Params& P, int b, int h, int qb, unsigned char* smem) {
;     ...
;         if (MODE == 1) {
; #pragma unroll
;           for (int g = 0; g < 4; ++g) {
;             const f32x4 c4 = *(const f32x4*)(smem + cur + 20480 + (32 * kb + 8 * g + 4 * hi) * 4);
;             c0[4 * g] = c4[0]; c0[4 * g + 1] = c4[1]; c0[4 * g + 2] = c4[2]; c0[4 * g + 3] = c4[3];
;           }
;         } else {
; #pragma unroll
;           for (int i = 0; i < 16; ++i) c0[i] = 0.f;
;         }
;         sacc[kb] = c0;
; #pragma unroll
;         for (int ks = 0; ks < 4; ++ks) {
;           bf16x8 kf = *(const bf16x8*)(smem + cur + (32 * kb + r) * 128 + (((2 * ks + hi) ^ swz) << 4));
;           sacc[kb] = __builtin_amdgcn_mfma_f32_32x32x16_bf16(kf, qf[ks], sacc[kb], 0, 0, 0);
;         }
;         if (MODE == 0) {
; #pragma unroll
;           for (int ks = 0; ks < 2; ++ks) {
;             bf16x8 kf = *(const bf16x8*)(smem + cur + 16384 + (32 * kb + r) * 64 + (((2 * ks + hi) ^ swr) << 4));
;             sacc[kb] = __builtin_amdgcn_mfma_f32_32x32x16_bf16(kf, qf[4 + ks], sacc[kb], 0, 0, 0);
;           }
;         }
;       }
;       if (MODE == 2) {
; #pragma unroll
;         for (int kb = 0; kb < 2; ++kb)
; #pragma unroll
;           for (int i = 0; i < 16; ++i) {
;             const int key = k0 + 32 * kb + 8 * (i >> 2) + 4 * hi + (i & 3);
;             const int dist = qi - key;
;             const float v = sacc[kb][i] - slope2 * (float)dist;
;             sacc[kb][i] = (dist >= 0 && dist < 128) ? v : -INFINITY;
;           }
;       } else if (k0 + 63 > qw0) {
; #pragma unroll
;         for (int kb = 0; kb < 2; ++kb)
; #pragma unroll
;           for (int i = 0; i < 16; ++i) {
;             const int key = k0 + 32 * kb + 8 * (i >> 2) + 4 * hi + (i & 3);
;             if (key > qi) sacc[kb][i] = -INFINITY;
;           }
;       }
.LBB0_1618:
	s_or_b64 exec, exec, s[16:17]
	s_bitcmp1_b32 s8, 0
	s_cselect_b32 s24, 0x5100, 0
	s_sub_i32 s16, s21, 63
	v_cmp_le_i32_e32 vcc, s16, v84
	s_and_saveexec_b64 s[16:17], vcc
	s_cbranch_execz .LBB0_1624
	s_add_i32 s18, s24, 0
	v_add_u32_e32 v36, s18, v128
	v_add_u32_e32 v44, s18, v114
	v_add_u32_e32 v85, v36, v129
	v_add_u32_e32 v86, v36, v127
	v_add_u32_e32 v87, v36, v126
	v_add_u32_e32 v88, v36, v125
	ds_read_b128 v[48:51], v44 offset:20480
	ds_read_b128 v[52:55], v44 offset:20512
	ds_read_b128 v[56:59], v44 offset:20544
	ds_read_b128 v[60:63], v44 offset:20576
	ds_read_b128 v[160:163], v85
	ds_read_b128 v[164:167], v86
	ds_read_b128 v[168:171], v87
	ds_read_b128 v[172:175], v88
	ds_read_b128 v[90:93], v85 offset:4096
	ds_read_b128 v[130:133], v86 offset:4096
	ds_read_b128 v[134:137], v87 offset:4096
	ds_read_b128 v[138:141], v88 offset:4096
	v_cmp_gt_i32_e32 vcc, s21, v124
	s_waitcnt lgkmcnt(7)
	v_mfma_f32_32x32x16_bf16 v[48:63], v[160:163], v[100:103], v[48:63]
	ds_read_b128 v[32:35], v44 offset:20608
	ds_read_b128 v[36:39], v44 offset:20640
	ds_read_b128 v[40:43], v44 offset:20672
	ds_read_b128 v[44:47], v44 offset:20704
	s_waitcnt lgkmcnt(10)
	v_mfma_f32_32x32x16_bf16 v[48:63], v[164:167], v[104:107], v[48:63]
	s_waitcnt lgkmcnt(9)
	v_mfma_f32_32x32x16_bf16 v[48:63], v[168:171], v[108:111], v[48:63]
	s_waitcnt lgkmcnt(8)
	v_mfma_f32_32x32x16_bf16 v[48:63], v[172:175], v[96:99], v[48:63]
	s_waitcnt lgkmcnt(0)
	v_mfma_f32_32x32x16_bf16 v[32:47], v[90:93], v[100:103], v[32:47]
	v_mfma_f32_32x32x16_bf16 v[32:47], v[130:133], v[104:107], v[32:47]
	v_mfma_f32_32x32x16_bf16 v[32:47], v[134:137], v[108:111], v[32:47]
	v_mfma_f32_32x32x16_bf16 v[32:47], v[138:141], v[96:99], v[32:47]
	s_and_saveexec_b64 s[18:19], vcc
	s_cbranch_execz .LBB0_1621
	v_add_u32_e32 v89, s21, v121
	v_subrev_u32_e32 v90, 63, v89
	v_cmp_gt_i32_e32 vcc, v90, v120
	s_nop 1
	v_cndmask_b32_e32 v91, v48, v119, vcc
	v_cmp_lt_i32_e32 vcc, v90, v120
	v_subrev_u32_e32 v90, 61, v89
	s_nop 0
	v_cndmask_b32_e32 v48, v91, v48, vcc
	v_cndmask_b32_e32 v49, v119, v49, vcc
	v_cmp_le_i32_e32 vcc, v90, v120
	v_subrev_u32_e32 v90, 60, v89
	s_nop 0
	v_cndmask_b32_e32 v50, v119, v50, vcc
	v_cmp_le_i32_e32 vcc, v90, v120
	v_subrev_u32_e32 v90, 55, v89
	s_nop 0
	v_cndmask_b32_e32 v51, v119, v51, vcc
	v_cmp_le_i32_e32 vcc, v90, v120
	v_subrev_u32_e32 v90, 54, v89
	s_nop 0
	v_cndmask_b32_e32 v52, v119, v52, vcc
	v_cmp_le_i32_e32 vcc, v90, v120
	v_subrev_u32_e32 v90, 53, v89
	s_nop 0
	v_cndmask_b32_e32 v53, v119, v53, vcc
	v_cmp_le_i32_e32 vcc, v90, v120
	v_subrev_u32_e32 v90, 52, v89
	s_nop 0
	v_cndmask_b32_e32 v54, v119, v54, vcc
	v_cmp_le_i32_e32 vcc, v90, v120
	v_subrev_u32_e32 v90, 47, v89
	s_nop 0
	v_cndmask_b32_e32 v55, v119, v55, vcc
	v_cmp_le_i32_e32 vcc, v90, v120
	v_subrev_u32_e32 v90, 46, v89
	s_nop 0
	v_cndmask_b32_e32 v56, v119, v56, vcc
	v_cmp_le_i32_e32 vcc, v90, v120
	v_subrev_u32_e32 v90, 45, v89
	s_nop 0
	v_cndmask_b32_e32 v57, v119, v57, vcc
	v_cmp_le_i32_e32 vcc, v90, v120
	v_subrev_u32_e32 v90, 44, v89
	s_nop 0
	v_cndmask_b32_e32 v58, v119, v58, vcc
	v_cmp_le_i32_e32 vcc, v90, v120
	v_subrev_u32_e32 v90, 39, v89
	s_nop 0
	v_cndmask_b32_e32 v59, v119, v59, vcc
	v_cmp_le_i32_e32 vcc, v90, v120
	v_subrev_u32_e32 v90, 38, v89
	s_nop 0
	v_cndmask_b32_e32 v60, v119, v60, vcc
	v_cmp_le_i32_e32 vcc, v90, v120
	v_subrev_u32_e32 v90, 37, v89
	s_nop 0
	v_cndmask_b32_e32 v61, v119, v61, vcc
	v_cmp_le_i32_e32 vcc, v90, v120
	v_subrev_u32_e32 v90, 36, v89
	s_nop 0
	v_cndmask_b32_e32 v62, v119, v62, vcc
	v_cmp_le_i32_e32 vcc, v90, v120
	v_subrev_u32_e32 v90, 31, v89
	s_nop 0
	v_cndmask_b32_e32 v63, v119, v63, vcc
	v_cmp_le_i32_e32 vcc, v90, v120
	v_subrev_u32_e32 v90, 30, v89
	s_nop 0
	v_cndmask_b32_e32 v32, v119, v32, vcc
	v_cmp_le_i32_e32 vcc, v90, v120
	v_subrev_u32_e32 v90, 29, v89
	s_nop 0
	v_cndmask_b32_e32 v33, v119, v33, vcc
	v_cmp_le_i32_e32 vcc, v90, v120
	v_subrev_u32_e32 v90, 28, v89
	s_nop 0
	v_cndmask_b32_e32 v34, v119, v34, vcc
	v_cmp_le_i32_e32 vcc, v90, v120
	v_subrev_u32_e32 v90, 23, v89
	s_nop 0
	v_cndmask_b32_e32 v35, v119, v35, vcc
	v_cmp_le_i32_e32 vcc, v90, v120
	v_subrev_u32_e32 v90, 22, v89
	s_nop 0
	v_cndmask_b32_e32 v36, v119, v36, vcc
	v_cmp_le_i32_e32 vcc, v90, v120
	v_subrev_u32_e32 v90, 21, v89
	s_nop 0
	v_cndmask_b32_e32 v37, v119, v37, vcc
	v_cmp_le_i32_e32 vcc, v90, v120
	v_subrev_u32_e32 v90, 20, v89
	s_nop 0
	v_cndmask_b32_e32 v38, v119, v38, vcc
	v_cmp_le_i32_e32 vcc, v90, v120
	v_add_u32_e32 v90, -15, v89
	s_nop 0
	v_cndmask_b32_e32 v39, v119, v39, vcc
	v_cmp_le_i32_e32 vcc, v90, v120
	v_add_u32_e32 v90, -14, v89
	s_nop 0
	v_cndmask_b32_e32 v40, v119, v40, vcc
	v_cmp_le_i32_e32 vcc, v90, v120
	v_add_u32_e32 v90, -13, v89
	s_nop 0
	v_cndmask_b32_e32 v41, v119, v41, vcc
	v_cmp_le_i32_e32 vcc, v90, v120
	v_add_u32_e32 v90, -12, v89
	s_nop 0
	v_cndmask_b32_e32 v42, v119, v42, vcc
	v_cmp_le_i32_e32 vcc, v90, v120
	v_add_u32_e32 v90, -7, v89
	s_nop 0
	v_cndmask_b32_e32 v43, v119, v43, vcc
	v_cmp_le_i32_e32 vcc, v90, v120
	v_add_u32_e32 v90, -6, v89
	s_nop 0
	v_cndmask_b32_e32 v44, v119, v44, vcc
	v_cmp_le_i32_e32 vcc, v90, v120
	v_add_u32_e32 v90, -5, v89
	v_add_u32_e32 v89, -4, v89
	v_cndmask_b32_e32 v45, v119, v45, vcc
	v_cmp_le_i32_e32 vcc, v90, v120
	s_nop 1
	v_cndmask_b32_e32 v46, v119, v46, vcc
	v_cmp_le_i32_e32 vcc, v89, v120
	s_nop 1
	v_cndmask_b32_e32 v47, v119, v47, vcc
; __device__ __forceinline__ float fast_exp2(float x) { return __builtin_amdgcn_exp2f(x); }
; template <int MODE>
; __device__ __forceinline__ void attn_unit(const Params& P, int b, int h, int qb, unsigned char* smem) {
;     ...
;       float mx = sacc[0][0];
; #pragma unroll
;       for (int i = 1; i < 16; ++i) mx = fmaxf(mx, sacc[0][i]);
; #pragma unroll
;       for (int i = 0; i < 16; ++i) mx = fmaxf(mx, sacc[1][i]);
;       mx = fmaxf(mx, __shfl_xor(mx, 32));
;       if (__any(mx > m_run + 24.0f)) {
;         const float m_new = fmaxf(m_run, mx);
;         const float alpha = fast_exp2(m_run - m_new);
;         m_run = m_new; l_run *= alpha;
;         const f32x2_t a2 = {alpha, alpha};
; #pragma unroll
;         for (int i = 0; i < 8; ++i) {
;           f32x2_t t0 = {oacc[0][2 * i], oacc[0][2 * i + 1]}, t1 = {oacc[1][2 * i], oacc[1][2 * i + 1]};
;           t0 *= a2; t1 *= a2;
;           oacc[0][2 * i] = t0[0]; oacc[0][2 * i + 1] = t0[1]; oacc[1][2 * i] = t1[0]; oacc[1][2 * i + 1] = t1[1];
;         }
;       }
.LBB0_1621:
	s_or_b64 exec, exec, s[18:19]
	s_nop 3
	v_max_f32_e32 v89, v49, v49
	v_max_f32_e32 v90, v48, v48
	v_max_f32_e32 v89, v90, v89
	v_max3_f32 v89, v89, v50, v51
	v_max3_f32 v89, v89, v52, v53
	v_max3_f32 v89, v89, v54, v55
	v_max3_f32 v89, v89, v56, v57
	v_max3_f32 v89, v89, v58, v59
	v_max3_f32 v89, v89, v60, v61
	v_max3_f32 v89, v89, v62, v63
	v_max3_f32 v89, v89, v32, v33
	v_max3_f32 v89, v89, v34, v35
	v_max3_f32 v89, v89, v36, v37
	v_max3_f32 v89, v89, v38, v39
	v_max3_f32 v89, v89, v40, v41
	v_max3_f32 v89, v89, v42, v43
	v_max3_f32 v89, v89, v44, v45
	v_max3_f32 v89, v89, v46, v47
	v_mov_b32_e32 v90, v89
	s_nop 1
	v_permlane32_swap_b32_e32 v90, v89
	v_max_f32_e32 v89, v89, v90
	v_add_f32_e32 v90, 0x41c00000, v118
	v_cmp_gt_f32_e32 vcc, v89, v90
	s_cbranch_vccz .LBB0_1623
	v_max_f32_e32 v89, v89, v89
	v_max_f32_e32 v90, v118, v118
	v_max_f32_e32 v89, v90, v89
	v_sub_f32_e32 v90, v118, v89
	v_exp_f32_e32 v90, v90
	v_mov_b32_e32 v118, v89
	v_pk_mul_f32 v[30:31], v[30:31], v[90:91] op_sel_hi:[1,0]
	v_pk_mul_f32 v[28:29], v[28:29], v[90:91] op_sel_hi:[1,0]
	v_pk_mul_f32 v[26:27], v[26:27], v[90:91] op_sel_hi:[1,0]
	v_pk_mul_f32 v[24:25], v[24:25], v[90:91] op_sel_hi:[1,0]
	v_pk_mul_f32 v[22:23], v[22:23], v[90:91] op_sel_hi:[1,0]
	v_pk_mul_f32 v[20:21], v[20:21], v[90:91] op_sel_hi:[1,0]
	v_pk_mul_f32 v[18:19], v[18:19], v[90:91] op_sel_hi:[1,0]
	v_pk_mul_f32 v[16:17], v[16:17], v[90:91] op_sel_hi:[1,0]
	v_pk_mul_f32 v[14:15], v[14:15], v[90:91] op_sel_hi:[1,0]
	v_pk_mul_f32 v[12:13], v[12:13], v[90:91] op_sel_hi:[1,0]
	v_pk_mul_f32 v[10:11], v[10:11], v[90:91] op_sel_hi:[1,0]
	v_pk_mul_f32 v[8:9], v[8:9], v[90:91] op_sel_hi:[1,0]
	v_pk_mul_f32 v[6:7], v[6:7], v[90:91] op_sel_hi:[1,0]
	v_pk_mul_f32 v[4:5], v[4:5], v[90:91] op_sel_hi:[1,0]
	v_pk_mul_f32 v[2:3], v[2:3], v[90:91] op_sel_hi:[1,0]
	v_pk_mul_f32 v[0:1], v[0:1], v[90:91] op_sel_hi:[1,0]
	v_mul_f32_e32 v123, v123, v90
